# GEMM3 fused epilogue: row-scale multiplies packed too (v_pk_mul_f32 with op_sel broadcast)
# speedup vs baseline: 1.0234x; 1.0014x over previous
;     __device__ __forceinline__ void operator()(const f32x4 (&acc)[2][2][4][2], const Unit& u, int wr, int wc, int fr, int fq) const {
;     ...
;         float rs[2][4];
; #pragma unroll
;         for (int ai = 0; ai < 2; ++ai)
; #pragma unroll
;             for (int m = 0; m < 4; ++m) rs[ai][m] = ssq ? rsqrtf(ssq[row0 + ai * HALF + m * 16] * (1.f / DM) + EPS) : 1.f;
; #pragma unroll
;         for (int ai = 0; ai < 2; ++ai)
; #pragma unroll
;             for (int m = 0; m < 4; ++m) { bf16_t* rowp = O + (size_t)(row0 + ai * HALF + m * 16) * ldc + col0;
; #pragma unroll
;                 for (int bj = 0; bj < 2; ++bj) { const f32x4 v0 = acc[ai][bj][m][0] * rs[ai][m], v1 = acc[ai][bj][m][1] * rs[ai][m];
.Lepi7_rs:
	v_fmamk_f32 v158, v158, 0x3a000000, v157
	v_fmamk_f32 v159, v159, 0x3a000000, v157
	v_fmamk_f32 v160, v160, 0x3a000000, v157
	v_fmamk_f32 v161, v161, 0x3a000000, v157
	v_fmamk_f32 v162, v162, 0x3a000000, v157
	v_fmamk_f32 v163, v163, 0x3a000000, v157
	v_fmamk_f32 v164, v164, 0x3a000000, v157
	v_fmamk_f32 v165, v165, 0x3a000000, v157
	v_rsq_f32_e32 v158, v158
	v_rsq_f32_e32 v159, v159
	v_rsq_f32_e32 v160, v160
	v_rsq_f32_e32 v161, v161
	v_rsq_f32_e32 v162, v162
	v_rsq_f32_e32 v163, v163
	v_rsq_f32_e32 v164, v164
	v_rsq_f32_e32 v165, v165
	s_nop 0
	v_pk_mul_f32 v[112:113], v[112:113], v[158:159] op_sel:[0,0] op_sel_hi:[1,0]
	v_pk_mul_f32 v[114:115], v[114:115], v[158:159] op_sel:[0,0] op_sel_hi:[1,0]
	v_pk_mul_f32 v[116:117], v[116:117], v[158:159] op_sel:[0,0] op_sel_hi:[1,0]
	v_pk_mul_f32 v[118:119], v[118:119], v[158:159] op_sel:[0,0] op_sel_hi:[1,0]
	v_pk_mul_f32 v[120:121], v[120:121], v[158:159] op_sel:[0,0] op_sel_hi:[1,0]
	v_pk_mul_f32 v[122:123], v[122:123], v[158:159] op_sel:[0,0] op_sel_hi:[1,0]
	v_pk_mul_f32 v[124:125], v[124:125], v[158:159] op_sel:[0,0] op_sel_hi:[1,0]
	v_pk_mul_f32 v[126:127], v[126:127], v[158:159] op_sel:[0,0] op_sel_hi:[1,0]
	v_pk_mul_f32 v[96:97], v[96:97], v[158:159] op_sel:[0,1] op_sel_hi:[1,1]
	v_pk_mul_f32 v[98:99], v[98:99], v[158:159] op_sel:[0,1] op_sel_hi:[1,1]
	v_pk_mul_f32 v[100:101], v[100:101], v[158:159] op_sel:[0,1] op_sel_hi:[1,1]
	v_pk_mul_f32 v[102:103], v[102:103], v[158:159] op_sel:[0,1] op_sel_hi:[1,1]
	v_pk_mul_f32 v[104:105], v[104:105], v[158:159] op_sel:[0,1] op_sel_hi:[1,1]
	v_pk_mul_f32 v[106:107], v[106:107], v[158:159] op_sel:[0,1] op_sel_hi:[1,1]
	v_pk_mul_f32 v[108:109], v[108:109], v[158:159] op_sel:[0,1] op_sel_hi:[1,1]
	v_pk_mul_f32 v[110:111], v[110:111], v[158:159] op_sel:[0,1] op_sel_hi:[1,1]
	v_pk_mul_f32 v[80:81], v[80:81], v[160:161] op_sel:[0,0] op_sel_hi:[1,0]
	v_pk_mul_f32 v[82:83], v[82:83], v[160:161] op_sel:[0,0] op_sel_hi:[1,0]
	v_pk_mul_f32 v[84:85], v[84:85], v[160:161] op_sel:[0,0] op_sel_hi:[1,0]
	v_pk_mul_f32 v[86:87], v[86:87], v[160:161] op_sel:[0,0] op_sel_hi:[1,0]
	v_pk_mul_f32 v[88:89], v[88:89], v[160:161] op_sel:[0,0] op_sel_hi:[1,0]
	v_pk_mul_f32 v[90:91], v[90:91], v[160:161] op_sel:[0,0] op_sel_hi:[1,0]
	v_pk_mul_f32 v[92:93], v[92:93], v[160:161] op_sel:[0,0] op_sel_hi:[1,0]
	v_pk_mul_f32 v[94:95], v[94:95], v[160:161] op_sel:[0,0] op_sel_hi:[1,0]
	v_pk_mul_f32 v[64:65], v[64:65], v[160:161] op_sel:[0,1] op_sel_hi:[1,1]
	v_pk_mul_f32 v[66:67], v[66:67], v[160:161] op_sel:[0,1] op_sel_hi:[1,1]
	v_pk_mul_f32 v[68:69], v[68:69], v[160:161] op_sel:[0,1] op_sel_hi:[1,1]
	v_pk_mul_f32 v[70:71], v[70:71], v[160:161] op_sel:[0,1] op_sel_hi:[1,1]
	v_pk_mul_f32 v[72:73], v[72:73], v[160:161] op_sel:[0,1] op_sel_hi:[1,1]
	v_pk_mul_f32 v[74:75], v[74:75], v[160:161] op_sel:[0,1] op_sel_hi:[1,1]
	v_pk_mul_f32 v[76:77], v[76:77], v[160:161] op_sel:[0,1] op_sel_hi:[1,1]
	v_pk_mul_f32 v[78:79], v[78:79], v[160:161] op_sel:[0,1] op_sel_hi:[1,1]
	v_pk_mul_f32 v[48:49], v[48:49], v[162:163] op_sel:[0,0] op_sel_hi:[1,0]
	v_pk_mul_f32 v[50:51], v[50:51], v[162:163] op_sel:[0,0] op_sel_hi:[1,0]
	v_pk_mul_f32 v[52:53], v[52:53], v[162:163] op_sel:[0,0] op_sel_hi:[1,0]
	v_pk_mul_f32 v[54:55], v[54:55], v[162:163] op_sel:[0,0] op_sel_hi:[1,0]
	v_pk_mul_f32 v[56:57], v[56:57], v[162:163] op_sel:[0,0] op_sel_hi:[1,0]
	v_pk_mul_f32 v[58:59], v[58:59], v[162:163] op_sel:[0,0] op_sel_hi:[1,0]
	v_pk_mul_f32 v[60:61], v[60:61], v[162:163] op_sel:[0,0] op_sel_hi:[1,0]
	v_pk_mul_f32 v[62:63], v[62:63], v[162:163] op_sel:[0,0] op_sel_hi:[1,0]
	v_pk_mul_f32 v[32:33], v[32:33], v[162:163] op_sel:[0,1] op_sel_hi:[1,1]
	v_pk_mul_f32 v[34:35], v[34:35], v[162:163] op_sel:[0,1] op_sel_hi:[1,1]
	v_pk_mul_f32 v[36:37], v[36:37], v[162:163] op_sel:[0,1] op_sel_hi:[1,1]
	v_pk_mul_f32 v[38:39], v[38:39], v[162:163] op_sel:[0,1] op_sel_hi:[1,1]
	v_pk_mul_f32 v[40:41], v[40:41], v[162:163] op_sel:[0,1] op_sel_hi:[1,1]
	v_pk_mul_f32 v[42:43], v[42:43], v[162:163] op_sel:[0,1] op_sel_hi:[1,1]
	v_pk_mul_f32 v[44:45], v[44:45], v[162:163] op_sel:[0,1] op_sel_hi:[1,1]
	v_pk_mul_f32 v[46:47], v[46:47], v[162:163] op_sel:[0,1] op_sel_hi:[1,1]
	v_pk_mul_f32 v[16:17], v[16:17], v[164:165] op_sel:[0,0] op_sel_hi:[1,0]
	v_pk_mul_f32 v[18:19], v[18:19], v[164:165] op_sel:[0,0] op_sel_hi:[1,0]
	v_pk_mul_f32 v[20:21], v[20:21], v[164:165] op_sel:[0,0] op_sel_hi:[1,0]
	v_pk_mul_f32 v[22:23], v[22:23], v[164:165] op_sel:[0,0] op_sel_hi:[1,0]
	v_pk_mul_f32 v[24:25], v[24:25], v[164:165] op_sel:[0,0] op_sel_hi:[1,0]
	v_pk_mul_f32 v[26:27], v[26:27], v[164:165] op_sel:[0,0] op_sel_hi:[1,0]
	v_pk_mul_f32 v[28:29], v[28:29], v[164:165] op_sel:[0,0] op_sel_hi:[1,0]
	v_pk_mul_f32 v[30:31], v[30:31], v[164:165] op_sel:[0,0] op_sel_hi:[1,0]
	v_pk_mul_f32 v[0:1], v[0:1], v[164:165] op_sel:[0,1] op_sel_hi:[1,1]
	v_pk_mul_f32 v[2:3], v[2:3], v[164:165] op_sel:[0,1] op_sel_hi:[1,1]
	v_pk_mul_f32 v[4:5], v[4:5], v[164:165] op_sel:[0,1] op_sel_hi:[1,1]
	v_pk_mul_f32 v[6:7], v[6:7], v[164:165] op_sel:[0,1] op_sel_hi:[1,1]
	v_pk_mul_f32 v[8:9], v[8:9], v[164:165] op_sel:[0,1] op_sel_hi:[1,1]
	v_pk_mul_f32 v[10:11], v[10:11], v[164:165] op_sel:[0,1] op_sel_hi:[1,1]
	v_pk_mul_f32 v[12:13], v[12:13], v[164:165] op_sel:[0,1] op_sel_hi:[1,1]
	v_pk_mul_f32 v[14:15], v[14:15], v[164:165] op_sel:[0,1] op_sel_hi:[1,1]
	s_cmpk_ge_u32 s7, 32
	s_cbranch_scc1 .Lepi7_sample
; __device__ __forceinline__ unsigned cvt_pk_bf16(float lo, float hi) { unsigned r; asm volatile("v_cvt_pk_bf16_f32 %0, %1, %2" : "=v"(r) : "v"(lo), "v"(hi)); return r; }
; #define ST8(ptr, src) do { *(f32x4*)(ptr) = (f32x4){src[0], src[1], src[2], src[3]}; *(f32x4*)((ptr) + 4) = (f32x4){src[4], src[5], src[6], src[7]}; } while (0)
;     __device__ __forceinline__ void operator()(const f32x4 (&acc)[2][2][4][2], const Unit& u, int wr, int wc, int fr, int fq) const {
;     ...
;             for (int m = 0; m < 4; ++m) { bf16_t* rowp = O + (size_t)(row0 + ai * HALF + m * 16) * ldc + col0;
; #pragma unroll
;                 for (int bj = 0; bj < 2; ++bj) { const f32x4 v0 = acc[ai][bj][m][0] * rs[ai][m], v1 = acc[ai][bj][m][1] * rs[ai][m];
;                     u32x4 w; w.x = cvt_pk_bf16(v0[0], v0[1]); w.y = cvt_pk_bf16(v0[2], v0[3]); w.z = cvt_pk_bf16(v1[0], v1[1]); w.w = cvt_pk_bf16(v1[2], v1[3]);
;                     *(u32x4*)(rowp + bj * HALF) = w; } }
; template <int NT, bool SAMPLE>
; __device__ __forceinline__ void ffn_item(const bf16_t* U, int row0, bool has_hist, const float* st, int cgi, const float* w, const float* bias, bf16_t* ACT, float* state_out) {
;     ...
;     if (state_out) {
;     ...
;         ST8(state_out + 0 * FF2 + c0, g0); ST8(state_out + 1 * FF2 + c0, g1); ST8(state_out + 0 * FF2 + FF + c0, v0); ST8(state_out + 1 * FF2 + FF + c0, v1);
;     ...
;     }
	v_cvt_pk_bf16_f32 v168, v124, v125
	v_cvt_pk_bf16_f32 v169, v126, v127
	v_cvt_pk_bf16_f32 v170, v120, v121
	v_cvt_pk_bf16_f32 v171, v122, v123
	v_cvt_pk_bf16_f32 v172, v116, v117
	v_cvt_pk_bf16_f32 v173, v118, v119
	v_cvt_pk_bf16_f32 v174, v112, v113
	v_cvt_pk_bf16_f32 v175, v114, v115
	s_mov_b32 exec_lo, 0x00030003
	s_mov_b32 exec_hi, 0x00030003
	global_store_dwordx4 v152, v[168:171], s[10:11]
	global_store_dwordx4 v152, v[172:175], s[12:13]
	s_mov_b64 exec, -1
	s_add_u32 s10, s10, 0x5600
	s_addc_u32 s11, s11, 0
	s_add_u32 s12, s12, 0x5600
	s_addc_u32 s13, s13, 0
	v_cvt_pk_bf16_f32 v168, v108, v109
	v_cvt_pk_bf16_f32 v169, v110, v111
	v_cvt_pk_bf16_f32 v170, v104, v105
	v_cvt_pk_bf16_f32 v171, v106, v107
	v_cvt_pk_bf16_f32 v172, v100, v101
	v_cvt_pk_bf16_f32 v173, v102, v103
	v_cvt_pk_bf16_f32 v174, v96, v97
	v_cvt_pk_bf16_f32 v175, v98, v99
	s_mov_b32 exec_lo, 0x00030003
	s_mov_b32 exec_hi, 0x00030003
	global_store_dwordx4 v152, v[168:171], s[10:11]
	global_store_dwordx4 v152, v[172:175], s[12:13]
	s_mov_b64 exec, -1
	s_add_u32 s10, s10, 0x5600
	s_addc_u32 s11, s11, 0
	s_add_u32 s12, s12, 0x5600
	s_addc_u32 s13, s13, 0
	v_cvt_pk_bf16_f32 v168, v92, v93
	v_cvt_pk_bf16_f32 v169, v94, v95
	v_cvt_pk_bf16_f32 v170, v88, v89
	v_cvt_pk_bf16_f32 v171, v90, v91
	v_cvt_pk_bf16_f32 v172, v84, v85
	v_cvt_pk_bf16_f32 v173, v86, v87
	v_cvt_pk_bf16_f32 v174, v80, v81
	v_cvt_pk_bf16_f32 v175, v82, v83
	s_mov_b32 exec_lo, 0x80038003
	s_mov_b32 exec_hi, 0x80038003
	global_store_dwordx4 v152, v[168:171], s[10:11]
	global_store_dwordx4 v152, v[172:175], s[12:13]
	s_mov_b64 exec, -1
	s_add_u32 s10, s10, 0x5600
	s_addc_u32 s11, s11, 0
	s_add_u32 s12, s12, 0x5600
	s_addc_u32 s13, s13, 0
	v_cvt_pk_bf16_f32 v168, v76, v77
	v_cvt_pk_bf16_f32 v169, v78, v79
	v_cvt_pk_bf16_f32 v170, v72, v73
	v_cvt_pk_bf16_f32 v171, v74, v75
	v_cvt_pk_bf16_f32 v172, v68, v69
	v_cvt_pk_bf16_f32 v173, v70, v71
	v_cvt_pk_bf16_f32 v174, v64, v65
	v_cvt_pk_bf16_f32 v175, v66, v67
	s_mov_b32 exec_lo, 0x80038003
	s_mov_b32 exec_hi, 0x80038003
	global_store_dwordx4 v152, v[168:171], s[10:11]
	global_store_dwordx4 v152, v[172:175], s[12:13]
	s_mov_b64 exec, -1
	s_add_u32 s10, s10, 0x29fe00
	s_addc_u32 s11, s11, 0
	s_add_u32 s12, s12, 0x29fe00
	s_addc_u32 s13, s13, 0
	v_cvt_pk_bf16_f32 v168, v60, v61
	v_cvt_pk_bf16_f32 v169, v62, v63
	v_cvt_pk_bf16_f32 v170, v56, v57
	v_cvt_pk_bf16_f32 v171, v58, v59
	v_cvt_pk_bf16_f32 v172, v52, v53
	v_cvt_pk_bf16_f32 v173, v54, v55
	v_cvt_pk_bf16_f32 v174, v48, v49
	v_cvt_pk_bf16_f32 v175, v50, v51
	s_mov_b32 exec_lo, 0x00030003
	s_mov_b32 exec_hi, 0x00030003
	global_store_dwordx4 v152, v[168:171], s[10:11]
	global_store_dwordx4 v152, v[172:175], s[12:13]
	s_mov_b64 exec, -1
	s_add_u32 s10, s10, 0x5600
	s_addc_u32 s11, s11, 0
	s_add_u32 s12, s12, 0x5600
	s_addc_u32 s13, s13, 0
	v_cvt_pk_bf16_f32 v168, v44, v45
	v_cvt_pk_bf16_f32 v169, v46, v47
	v_cvt_pk_bf16_f32 v170, v40, v41
	v_cvt_pk_bf16_f32 v171, v42, v43
	v_cvt_pk_bf16_f32 v172, v36, v37
	v_cvt_pk_bf16_f32 v173, v38, v39
	v_cvt_pk_bf16_f32 v174, v32, v33
	v_cvt_pk_bf16_f32 v175, v34, v35
	s_mov_b32 exec_lo, 0x00030003
	s_mov_b32 exec_hi, 0x00030003
	global_store_dwordx4 v152, v[168:171], s[10:11]
	global_store_dwordx4 v152, v[172:175], s[12:13]
	s_mov_b64 exec, -1
	s_add_u32 s10, s10, 0x5600
	s_addc_u32 s11, s11, 0
	s_add_u32 s12, s12, 0x5600
	s_addc_u32 s13, s13, 0
	v_cvt_pk_bf16_f32 v168, v28, v29
	v_cvt_pk_bf16_f32 v169, v30, v31
	v_cvt_pk_bf16_f32 v170, v24, v25
	v_cvt_pk_bf16_f32 v171, v26, v27
	v_cvt_pk_bf16_f32 v172, v20, v21
	v_cvt_pk_bf16_f32 v173, v22, v23
	v_cvt_pk_bf16_f32 v174, v16, v17
	v_cvt_pk_bf16_f32 v175, v18, v19
	s_mov_b32 exec_lo, 0x80038003
	s_mov_b32 exec_hi, 0x80038003
	global_store_dwordx4 v152, v[168:171], s[10:11]
	global_store_dwordx4 v152, v[172:175], s[12:13]
	s_mov_b64 exec, -1
	s_cmp_eq_u32 s60, 0
	s_cbranch_scc1 .Lepi7_nostate2
	v_lshlrev_b32_e32 v244, 16, v168
	v_and_b32_e32 v245, 0xffff0000, v168
	v_lshlrev_b32_e32 v246, 16, v169
	v_and_b32_e32 v247, 0xffff0000, v169
	v_lshlrev_b32_e32 v248, 16, v170
	v_and_b32_e32 v249, 0xffff0000, v170
	v_lshlrev_b32_e32 v250, 16, v171
	v_and_b32_e32 v251, 0xffff0000, v171
	v_lshlrev_b32_e32 v144, 16, v172
	v_and_b32_e32 v145, 0xffff0000, v172
	v_lshlrev_b32_e32 v137, 16, v173
	v_and_b32_e32 v166, 0xffff0000, v173
	v_lshlrev_b32_e32 v167, 16, v174
	v_and_b32_e32 v213, 0xffff0000, v174
	v_lshlrev_b32_e32 v214, 16, v175
	v_and_b32_e32 v215, 0xffff0000, v175
	s_mov_b32 exec_lo, 0x80008000
	s_mov_b32 exec_hi, 0x80008000
	v_mov_b32_e32 v168, v244
	v_mov_b32_e32 v169, v245
	v_mov_b32_e32 v170, v246
	v_mov_b32_e32 v171, v247
	global_store_dwordx4 v149, v[168:171], s[62:63] offset:0
	s_nop 1
	v_mov_b32_e32 v172, v248
	v_mov_b32_e32 v173, v249
	v_mov_b32_e32 v174, v250
	v_mov_b32_e32 v175, v251
	global_store_dwordx4 v149, v[172:175], s[62:63] offset:16
	s_nop 1
	v_mov_b32_e32 v168, v144
	v_mov_b32_e32 v169, v145
	v_mov_b32_e32 v170, v137
	v_mov_b32_e32 v171, v166
	global_store_dwordx4 v149, v[168:171], s[64:65] offset:0
	s_nop 1
	v_mov_b32_e32 v172, v167
	v_mov_b32_e32 v173, v213
	v_mov_b32_e32 v174, v214
	v_mov_b32_e32 v175, v215
	global_store_dwordx4 v149, v[172:175], s[64:65] offset:16
	s_nop 1
	s_mov_b64 exec, -1
